# in-proj K-loop head aligned to 64 bytes (code placement), on top of the attention priority/trim version
# baseline (speedup 1.0000x reference)
;     __device__ bool next(int i, Unit& u) const { const int t = c + i * nb; if (t >= 128) return false; u.pm = t & 31; u.pn = 88 + (t >> 5); return true; }
; template <class Epi, class Sched, bool ALIGN_EPI = false, bool SP2 = false>
; __device__ __forceinline__ void gemm_phase(PG8_LAS unsigned char* lds, const Gemm g, const Sched& S, const Epi& E) {
;     ...
;         const bool has_next = S.next(ui + 1, nxt);
;         const char* nA = has_next ? (const char*)g.A + (size_t)nxt.pm * tstep : cA; const char* nB = has_next ? (const char*)g.Bt + (size_t)nxt.pn * tstep : cB;
;         for (int t = 0; t < nt; t += 2) {
;             const bool last = (t == nt - 2);
;             const char* a1 = cA + (size_t)(t + 1) * kstep;
;             const char* a2 = last ? nA : cA + (size_t)(t + 2) * kstep; const char* b2 = last ? nB : cB + (size_t)(t + 2) * kstep;
;             const char* a3 = a2 + kstep; const char* b3 = b2 + kstep;
;     ...
; #pragma unroll
;         for (int a = 0; a < 2; ++a)
; #pragma unroll
;             for (int b = 0; b < 2; ++b)
; #pragma unroll
;                 for (int m = 0; m < 4; ++m)
; #pragma unroll
;                     for (int n = 0; n < 2; ++n) acc[a][b][m][n] = (f32x4){0.f, 0.f, 0.f, 0.f};
.LBB0_227:
	s_ashr_i32 s17, s16, 31
	s_lshl_b64 s[18:19], s[16:17], 20
	s_add_u32 s18, s24, s18
	s_addc_u32 s19, s25, s19
	s_and_b64 s[20:21], s[6:7], exec
	s_cselect_b32 s17, s19, s5
	s_cselect_b32 s40, s18, s4
	s_ashr_i32 s15, s14, 31
	s_lshl_b64 s[20:21], s[14:15], 20
	s_add_u32 s20, s26, s20
	s_addc_u32 s21, s27, s21
	s_and_b64 s[22:23], s[6:7], exec
	s_cselect_b32 s15, s21, s1
	s_cselect_b32 s41, s20, s0
	s_add_u32 s22, s4, 0x80080
	s_addc_u32 s23, s5, 0
	s_add_u32 s42, s0, 0x100
	v_mov_b32_e32 v2, 0
	s_addc_u32 s43, s1, 0
	s_mov_b32 s47, -2
	v_mov_b32_e32 v3, v2
	v_mov_b32_e32 v4, v2
	v_mov_b32_e32 v5, v2
	v_mov_b32_e32 v6, v2
	v_mov_b32_e32 v7, v2
	v_mov_b32_e32 v8, v2
	v_mov_b32_e32 v9, v2
	v_mov_b32_e32 v14, v2
	v_mov_b32_e32 v15, v2
	v_mov_b32_e32 v16, v2
	v_mov_b32_e32 v17, v2
	v_mov_b32_e32 v22, v2
	v_mov_b32_e32 v23, v2
	v_mov_b32_e32 v24, v2
	v_mov_b32_e32 v25, v2
	v_mov_b32_e32 v30, v2
	v_mov_b32_e32 v31, v2
	v_mov_b32_e32 v32, v2
	v_mov_b32_e32 v33, v2
	v_mov_b32_e32 v38, v2
	v_mov_b32_e32 v39, v2
	v_mov_b32_e32 v40, v2
	v_mov_b32_e32 v41, v2
	v_mov_b32_e32 v46, v2
	v_mov_b32_e32 v47, v2
	v_mov_b32_e32 v48, v2
	v_mov_b32_e32 v49, v2
	v_mov_b32_e32 v54, v2
	v_mov_b32_e32 v55, v2
	v_mov_b32_e32 v56, v2
	v_mov_b32_e32 v57, v2
	v_mov_b32_e32 v10, v2
	v_mov_b32_e32 v11, v2
	v_mov_b32_e32 v12, v2
	v_mov_b32_e32 v13, v2
	v_mov_b32_e32 v18, v2
	v_mov_b32_e32 v19, v2
	v_mov_b32_e32 v20, v2
	v_mov_b32_e32 v21, v2
	v_mov_b32_e32 v26, v2
	v_mov_b32_e32 v27, v2
	v_mov_b32_e32 v28, v2
	v_mov_b32_e32 v29, v2
	v_mov_b32_e32 v34, v2
	v_mov_b32_e32 v35, v2
	v_mov_b32_e32 v36, v2
	v_mov_b32_e32 v37, v2
	v_mov_b32_e32 v42, v2
	v_mov_b32_e32 v43, v2
	v_mov_b32_e32 v44, v2
	v_mov_b32_e32 v45, v2
	v_mov_b32_e32 v50, v2
	v_mov_b32_e32 v51, v2
	v_mov_b32_e32 v52, v2
	v_mov_b32_e32 v53, v2
	v_mov_b32_e32 v58, v2
	v_mov_b32_e32 v59, v2
	v_mov_b32_e32 v60, v2
	v_mov_b32_e32 v61, v2
	v_mov_b32_e32 v62, v2
	v_mov_b32_e32 v63, v2
	v_mov_b32_e32 v64, v2
	v_mov_b32_e32 v65, v2
	v_mov_b32_e32 v66, v2
	v_mov_b32_e32 v67, v2
	v_mov_b32_e32 v68, v2
	v_mov_b32_e32 v69, v2
	v_mov_b32_e32 v70, v2
	v_mov_b32_e32 v71, v2
	v_mov_b32_e32 v72, v2
	v_mov_b32_e32 v73, v2
	v_mov_b32_e32 v78, v2
	v_mov_b32_e32 v79, v2
	v_mov_b32_e32 v80, v2
	v_mov_b32_e32 v81, v2
	v_mov_b32_e32 v86, v2
	v_mov_b32_e32 v87, v2
	v_mov_b32_e32 v88, v2
	v_mov_b32_e32 v89, v2
	v_mov_b32_e32 v94, v2
	v_mov_b32_e32 v95, v2
	v_mov_b32_e32 v96, v2
	v_mov_b32_e32 v97, v2
	v_mov_b32_e32 v102, v2
	v_mov_b32_e32 v103, v2
	v_mov_b32_e32 v104, v2
	v_mov_b32_e32 v105, v2
	v_mov_b32_e32 v110, v2
	v_mov_b32_e32 v111, v2
	v_mov_b32_e32 v112, v2
	v_mov_b32_e32 v113, v2
	v_mov_b32_e32 v118, v2
	v_mov_b32_e32 v119, v2
	v_mov_b32_e32 v120, v2
	v_mov_b32_e32 v121, v2
	v_mov_b32_e32 v74, v2
	v_mov_b32_e32 v75, v2
	v_mov_b32_e32 v76, v2
	v_mov_b32_e32 v77, v2
	v_mov_b32_e32 v82, v2
	v_mov_b32_e32 v83, v2
	v_mov_b32_e32 v84, v2
	v_mov_b32_e32 v85, v2
	v_mov_b32_e32 v90, v2
	v_mov_b32_e32 v91, v2
	v_mov_b32_e32 v92, v2
	v_mov_b32_e32 v93, v2
	v_mov_b32_e32 v98, v2
	v_mov_b32_e32 v99, v2
	v_mov_b32_e32 v100, v2
	v_mov_b32_e32 v101, v2
	v_mov_b32_e32 v106, v2
	v_mov_b32_e32 v107, v2
	v_mov_b32_e32 v108, v2
	v_mov_b32_e32 v109, v2
	v_mov_b32_e32 v114, v2
	v_mov_b32_e32 v115, v2
	v_mov_b32_e32 v116, v2
	v_mov_b32_e32 v117, v2
	v_mov_b32_e32 v122, v2
	v_mov_b32_e32 v123, v2
	v_mov_b32_e32 v124, v2
	v_mov_b32_e32 v125, v2
	v_mov_b32_e32 v126, v2
	v_mov_b32_e32 v127, v2
	v_mov_b32_e32 v128, v2
	v_mov_b32_e32 v129, v2
	v_add_u32_e32 v144, 0x10000, v146
	.p2align 6
